# adds: non-leader workgroups poll the cross-XCD release generation directly (one hop less per grid barrier)
# speedup vs baseline: 1.0168x; 1.0018x over previous
.LBB0_147:
	s_or_b64 exec, exec, s[16:17]
	v_cvt_f32_u32_e32 v4, v2
	s_waitcnt vmcnt(0)
	v_readfirstlane_b32 s3, v3
	v_sub_u32_e32 v3, 0, v2
	v_rcp_iflag_f32_e32 v4, v4
	v_add_u32_e32 v5, s3, v1
	v_mul_f32_e32 v4, 0x4f7ffffe, v4
	v_cvt_u32_f32_e32 v4, v4
	v_mul_lo_u32 v1, v3, v4
	v_mul_hi_u32 v1, v4, v1
	v_add_u32_e32 v1, v4, v1
	v_mul_hi_u32 v1, v5, v1
	v_mul_lo_u32 v3, v1, v2
	v_sub_u32_e32 v3, v5, v3
	v_add_u32_e32 v4, 1, v1
	v_cmp_ge_u32_e32 vcc, v3, v2
	s_nop 1
	v_cndmask_b32_e32 v1, v1, v4, vcc
	v_sub_u32_e32 v4, v3, v2
	v_cndmask_b32_e32 v3, v3, v4, vcc
	v_add_u32_e32 v4, 1, v1
	v_cmp_ge_u32_e32 vcc, v3, v2
	v_add_u32_e32 v3, 1, v5
	s_nop 0
	v_cndmask_b32_e32 v1, v1, v4, vcc
	v_mul_lo_u32 v4, v2, v1
	v_add_u32_e32 v2, v4, v2
	v_cmp_ne_u32_e32 vcc, v3, v2
	s_and_saveexec_b64 s[8:9], vcc
	s_xor_b64 s[8:9], exec, s[8:9]
	s_cbranch_execz .LBB0_161
	s_waitcnt lgkmcnt(0)
	v_mov_b32_e32 v0, 0x3100
	global_load_dword v0, v0, s[80:81] offset:1024 sc1
	s_add_u32 s20, s80, 0x3500
	s_addc_u32 s21, s81, 0
	s_waitcnt vmcnt(0)
	v_cmp_eq_u32_e32 vcc, v0, v1
	s_and_saveexec_b64 s[16:17], vcc
	s_cbranch_execz .LBB0_160
	s_add_u32 s18, s88, 0x10200
	s_addc_u32 s19, s89, 0
	s_mov_b32 s3, 1
	s_mov_b64 s[22:23], 0
	v_mov_b32_e32 v0, 0
	s_branch .LBB0_151

.LBB0_279:
	s_or_b64 exec, exec, s[10:11]
	v_cvt_f32_u32_e32 v4, v2
	s_waitcnt vmcnt(0)
	v_readfirstlane_b32 s3, v3
	v_sub_u32_e32 v3, 0, v2
	v_rcp_iflag_f32_e32 v4, v4
	v_add_u32_e32 v5, s3, v1
	v_mul_f32_e32 v4, 0x4f7ffffe, v4
	v_cvt_u32_f32_e32 v4, v4
	v_mul_lo_u32 v1, v3, v4
	v_mul_hi_u32 v1, v4, v1
	v_add_u32_e32 v1, v4, v1
	v_mul_hi_u32 v1, v5, v1
	v_mul_lo_u32 v3, v1, v2
	v_sub_u32_e32 v3, v5, v3
	v_add_u32_e32 v4, 1, v1
	v_cmp_ge_u32_e32 vcc, v3, v2
	s_nop 1
	v_cndmask_b32_e32 v1, v1, v4, vcc
	v_sub_u32_e32 v4, v3, v2
	v_cndmask_b32_e32 v3, v3, v4, vcc
	v_add_u32_e32 v4, 1, v1
	v_cmp_ge_u32_e32 vcc, v3, v2
	v_add_u32_e32 v3, 1, v5
	s_nop 0
	v_cndmask_b32_e32 v1, v1, v4, vcc
	v_mul_lo_u32 v4, v2, v1
	v_add_u32_e32 v2, v4, v2
	v_cmp_ne_u32_e32 vcc, v3, v2
	s_and_saveexec_b64 s[8:9], vcc
	s_xor_b64 s[8:9], exec, s[8:9]
	s_cbranch_execz .LBB0_293
	s_waitcnt lgkmcnt(0)
	v_mov_b32_e32 v0, 0x3100
	global_load_dword v0, v0, s[80:81] offset:1024 sc1
	s_add_u32 s16, s80, 0x3500
	s_addc_u32 s17, s81, 0
	s_waitcnt vmcnt(0)
	v_cmp_eq_u32_e32 vcc, v0, v1
	s_and_saveexec_b64 s[10:11], vcc
	s_cbranch_execz .LBB0_292
	s_add_u32 s12, s88, 0x10200
	s_addc_u32 s13, s89, 0
	s_mov_b32 s3, 1
	s_mov_b64 s[18:19], 0
	v_mov_b32_e32 v0, 0
	s_branch .LBB0_283

.LBB0_449:
	s_or_b64 exec, exec, s[10:11]
	v_cvt_f32_u32_e32 v4, v2
	s_waitcnt vmcnt(0)
	v_readfirstlane_b32 s3, v3
	v_sub_u32_e32 v3, 0, v2
	v_rcp_iflag_f32_e32 v4, v4
	v_add_u32_e32 v5, s3, v1
	v_mul_f32_e32 v4, 0x4f7ffffe, v4
	v_cvt_u32_f32_e32 v4, v4
	v_mul_lo_u32 v1, v3, v4
	v_mul_hi_u32 v1, v4, v1
	v_add_u32_e32 v1, v4, v1
	v_mul_hi_u32 v1, v5, v1
	v_mul_lo_u32 v3, v1, v2
	v_sub_u32_e32 v3, v5, v3
	v_add_u32_e32 v4, 1, v1
	v_cmp_ge_u32_e32 vcc, v3, v2
	s_nop 1
	v_cndmask_b32_e32 v1, v1, v4, vcc
	v_sub_u32_e32 v4, v3, v2
	v_cndmask_b32_e32 v3, v3, v4, vcc
	v_add_u32_e32 v4, 1, v1
	v_cmp_ge_u32_e32 vcc, v3, v2
	v_add_u32_e32 v3, 1, v5
	s_nop 0
	v_cndmask_b32_e32 v1, v1, v4, vcc
	v_mul_lo_u32 v4, v2, v1
	v_add_u32_e32 v2, v4, v2
	v_cmp_ne_u32_e32 vcc, v3, v2
	s_and_saveexec_b64 s[8:9], vcc
	s_xor_b64 s[8:9], exec, s[8:9]
	s_cbranch_execz .LBB0_463
	s_waitcnt lgkmcnt(0)
	v_mov_b32_e32 v0, 0x3100
	global_load_dword v0, v0, s[80:81] offset:1024 sc1
	s_add_u32 s14, s80, 0x3500
	s_addc_u32 s15, s81, 0
	s_waitcnt vmcnt(0)
	v_cmp_eq_u32_e32 vcc, v0, v1
	s_and_saveexec_b64 s[10:11], vcc
	s_cbranch_execz .LBB0_462
	s_add_u32 s12, s88, 0x10200
	s_addc_u32 s13, s89, 0
	s_mov_b32 s3, 1
	s_mov_b64 s[16:17], 0
	v_mov_b32_e32 v0, 0
	s_branch .LBB0_453

.LBB0_627:
	s_or_b64 exec, exec, s[8:9]
	v_cvt_f32_u32_e32 v4, v2
	s_waitcnt vmcnt(0)
	v_readfirstlane_b32 s3, v3
	v_sub_u32_e32 v3, 0, v2
	v_rcp_iflag_f32_e32 v4, v4
	v_add_u32_e32 v5, s3, v1
	v_mul_f32_e32 v4, 0x4f7ffffe, v4
	v_cvt_u32_f32_e32 v4, v4
	v_mul_lo_u32 v1, v3, v4
	v_mul_hi_u32 v1, v4, v1
	v_add_u32_e32 v1, v4, v1
	v_mul_hi_u32 v1, v5, v1
	v_mul_lo_u32 v3, v1, v2
	v_sub_u32_e32 v3, v5, v3
	v_add_u32_e32 v4, 1, v1
	v_cmp_ge_u32_e32 vcc, v3, v2
	s_nop 1
	v_cndmask_b32_e32 v1, v1, v4, vcc
	v_sub_u32_e32 v4, v3, v2
	v_cndmask_b32_e32 v3, v3, v4, vcc
	v_add_u32_e32 v4, 1, v1
	v_cmp_ge_u32_e32 vcc, v3, v2
	v_add_u32_e32 v3, 1, v5
	s_nop 0
	v_cndmask_b32_e32 v1, v1, v4, vcc
	v_mul_lo_u32 v4, v2, v1
	v_add_u32_e32 v2, v4, v2
	v_cmp_ne_u32_e32 vcc, v3, v2
	s_and_saveexec_b64 s[6:7], vcc
	s_xor_b64 s[6:7], exec, s[6:7]
	s_cbranch_execz .LBB0_641
	s_waitcnt lgkmcnt(0)
	v_mov_b32_e32 v0, 0x3100
	global_load_dword v0, v0, s[80:81] offset:1024 sc1
	s_add_u32 s12, s80, 0x3500
	s_addc_u32 s13, s81, 0
	s_waitcnt vmcnt(0)
	v_cmp_eq_u32_e32 vcc, v0, v1
	s_and_saveexec_b64 s[8:9], vcc
	s_cbranch_execz .LBB0_640
	s_add_u32 s10, s88, 0x10200
	s_addc_u32 s11, s89, 0
	s_mov_b32 s3, 1
	s_mov_b64 s[16:17], 0
	v_mov_b32_e32 v0, 0
	s_branch .LBB0_631
